# v22: scan on 32 WGs + scan MFMA repipelined + P1/P8 wide-store epilogue + P6 transposes rebalanced + P6 tail-tile A loads trimmed
# speedup vs baseline: 1.0491x; 1.0099x over previous
.LBB0_3341:
	s_cmp_lg_u32 s41, 0
	s_cbranch_scc1 .Ltrim_LBB0_3341
	s_waitcnt vmcnt(0)
.Ltrim_LBB0_3341:
	s_bitcmp1_b32 s41, 0
	s_cselect_b32 s46, 0x12000, 0
	v_add3_u32 v150, s46, v67, v69
	v_add3_u32 v151, s46, v68, v69
	ds_read_b128 v[70:73], v150
	ds_read_b128 v[74:77], v151 offset:36864
	ds_read_b128 v[78:81], v150 offset:32
	ds_read_b128 v[130:133], v151 offset:36896
	ds_read_b128 v[134:137], v151 offset:41472
	ds_read_b128 v[138:141], v151 offset:41504
	s_waitcnt lgkmcnt(4)
	v_mfma_f32_32x32x16_bf16 v[114:129], v[70:73], v[74:77], v[114:129]
	s_add_i32 s41, s41, 1
	s_bitcmp1_b32 s41, 0
	s_cselect_b32 s46, 0x12000, 0
	v_add_u32_e32 v152, s46, v66
	v_lshl_add_u64 v[146:147], s[24:25], 0, v[54:55]
	v_lshl_add_u64 v[148:149], s[24:25], 0, v[56:57]
	s_waitcnt lgkmcnt(1)
	v_mfma_f32_32x32x16_bf16 v[98:113], v[70:73], v[134:137], v[98:113]
	ds_read_b128 v[70:73], v150 offset:4608
	ds_read_b128 v[142:145], v150 offset:4640
	s_waitcnt vmcnt(4)
	ds_write_b128 v152, v[2:5]
	ds_write_b128 v152, v[6:9] offset:9216
	s_waitcnt lgkmcnt(3)
	v_mfma_f32_32x32x16_bf16 v[82:97], v[70:73], v[74:77], v[82:97]
	v_mfma_f32_32x32x16_bf16 v[34:49], v[70:73], v[134:137], v[34:49]
	v_lshl_add_u64 v[70:71], s[24:25], 0, v[50:51]
	v_lshl_add_u64 v[72:73], s[24:25], 0, v[52:53]
	global_load_dwordx4 v[2:5], v[70:71], off
	v_mfma_f32_32x32x16_bf16 v[114:129], v[78:81], v[130:133], v[114:129]
	v_mfma_f32_32x32x16_bf16 v[98:113], v[78:81], v[138:141], v[98:113]
	ds_read_b128 v[70:73], v150 offset:64
	ds_read_b128 v[74:77], v150 offset:4672
	ds_read_b128 v[78:81], v151 offset:36928
	ds_read_b128 v[134:137], v151 offset:41536
	ds_write_b128 v152, v[10:13] offset:18432
	ds_write_b128 v152, v[14:17] offset:27648
	s_waitcnt lgkmcnt(8)
	v_mfma_f32_32x32x16_bf16 v[82:97], v[142:145], v[130:133], v[82:97]
	v_mfma_f32_32x32x16_bf16 v[34:49], v[142:145], v[138:141], v[34:49]
	v_lshl_add_u64 v[138:139], s[24:25], 0, v[58:59]
	v_lshl_add_u64 v[140:141], s[24:25], 0, v[62:63]
	v_lshl_add_u64 v[142:143], s[24:25], 0, v[60:61]
	v_lshl_add_u64 v[144:145], s[24:25], 0, v[64:65]
	s_waitcnt lgkmcnt(3)
	v_mfma_f32_32x32x16_bf16 v[114:129], v[70:73], v[78:81], v[114:129]
	s_waitcnt lgkmcnt(2)
	v_mfma_f32_32x32x16_bf16 v[98:113], v[70:73], v[134:137], v[98:113]
	v_mfma_f32_32x32x16_bf16 v[82:97], v[74:77], v[78:81], v[82:97]
	v_mfma_f32_32x32x16_bf16 v[34:49], v[74:77], v[134:137], v[34:49]
	ds_read_b128 v[70:73], v150 offset:96
	ds_read_b128 v[74:77], v151 offset:36960
	ds_read_b128 v[78:81], v150 offset:4704
	ds_read_b128 v[130:133], v151 offset:41568
	s_waitcnt vmcnt(4)
	ds_write_b128 v152, v[18:21] offset:36864
	s_waitcnt vmcnt(2)
	ds_write_b128 v152, v[22:25] offset:46080
	s_waitcnt vmcnt(3)
	ds_write_b128 v152, v[26:29] offset:55296
	s_waitcnt vmcnt(1)
	ds_write_b128 v152, v[30:33] offset:64512
	global_load_dwordx4 v[18:21], v[138:139], off
	global_load_dwordx4 v[26:29], v[140:141], off
	global_load_dwordx4 v[22:25], v[142:143], off
	global_load_dwordx4 v[30:33], v[144:145], off
	s_waitcnt lgkmcnt(6)
	v_mfma_f32_32x32x16_bf16 v[114:129], v[70:73], v[74:77], v[114:129]
	s_waitcnt lgkmcnt(4)
	v_mfma_f32_32x32x16_bf16 v[98:113], v[70:73], v[130:133], v[98:113]
	v_mfma_f32_32x32x16_bf16 v[82:97], v[78:81], v[74:77], v[82:97]
	v_mfma_f32_32x32x16_bf16 v[34:49], v[78:81], v[130:133], v[34:49]
	s_add_u32 s24, s24, 0x80
	s_addc_u32 s25, s25, 0
	s_cmp_eq_u32 s9, s41
	s_waitcnt lgkmcnt(0)
	s_barrier
	s_cbranch_scc0 .LBB0_3341
	s_cmp_ge_i32 s9, s40
	s_cbranch_scc0 .LBB0_3344
	s_branch .LBB0_3346

.LBB0_3345:
	s_bitcmp1_b32 s9, 0
	s_cselect_b32 s24, 0x12000, 0
	v_add3_u32 v53, s24, v50, v52
	v_add3_u32 v67, s24, v51, v52
	ds_read_b128 v[54:57], v53
	ds_read_b128 v[58:61], v67 offset:36864
	ds_read_b128 v[62:65], v53 offset:32
	ds_read_b128 v[68:71], v67 offset:36896
	ds_read_b128 v[72:75], v67 offset:41472
	ds_read_b128 v[76:79], v67 offset:41504
	s_waitcnt lgkmcnt(4)
	v_mfma_f32_32x32x16_bf16 v[114:129], v[54:57], v[58:61], v[114:129]
	s_add_i32 s9, s9, 1
	s_bitcmp1_b32 s9, 0
	s_cselect_b32 s24, 0x12000, 0
	s_waitcnt lgkmcnt(1)
	v_mfma_f32_32x32x16_bf16 v[98:113], v[54:57], v[72:75], v[98:113]
	ds_read_b128 v[54:57], v53 offset:4608
	ds_read_b128 v[130:133], v53 offset:4640
	s_waitcnt lgkmcnt(1)
	v_mfma_f32_32x32x16_bf16 v[82:97], v[54:57], v[58:61], v[82:97]
	v_mfma_f32_32x32x16_bf16 v[34:49], v[54:57], v[72:75], v[34:49]
	v_add_u32_e32 v72, s24, v66
	s_waitcnt vmcnt(4)
	ds_write_b128 v72, v[2:5]
	s_waitcnt vmcnt(6)
	ds_write_b128 v72, v[6:9] offset:9216
	ds_read_b128 v[54:57], v53 offset:64
	v_mfma_f32_32x32x16_bf16 v[114:129], v[62:65], v[68:71], v[114:129]
	v_mfma_f32_32x32x16_bf16 v[98:113], v[62:65], v[76:79], v[98:113]
	s_waitcnt lgkmcnt(3)
	v_mfma_f32_32x32x16_bf16 v[82:97], v[130:133], v[68:71], v[82:97]
	ds_read_b128 v[58:61], v53 offset:4672
	ds_read_b128 v[62:65], v67 offset:36928
	ds_read_b128 v[68:71], v67 offset:41536
	s_waitcnt vmcnt(5)
	ds_write_b128 v72, v[10:13] offset:18432
	s_waitcnt vmcnt(4)
	ds_write_b128 v72, v[14:17] offset:27648
	v_mfma_f32_32x32x16_bf16 v[34:49], v[130:133], v[76:79], v[34:49]
	s_waitcnt lgkmcnt(3)
	v_mfma_f32_32x32x16_bf16 v[114:129], v[54:57], v[62:65], v[114:129]
	s_waitcnt lgkmcnt(2)
	v_mfma_f32_32x32x16_bf16 v[98:113], v[54:57], v[68:71], v[98:113]
	v_mfma_f32_32x32x16_bf16 v[82:97], v[58:61], v[62:65], v[82:97]
	v_mfma_f32_32x32x16_bf16 v[34:49], v[58:61], v[68:71], v[34:49]
	ds_read_b128 v[54:57], v53 offset:96
	ds_read_b128 v[58:61], v67 offset:36960
	ds_read_b128 v[62:65], v53 offset:4704
	ds_read_b128 v[68:71], v67 offset:41568
	s_waitcnt vmcnt(3)
	ds_write_b128 v72, v[18:21] offset:36864
	s_waitcnt vmcnt(1)
	ds_write_b128 v72, v[22:25] offset:46080
	ds_write_b128 v72, v[26:29] offset:55296
	s_waitcnt vmcnt(0)
	ds_write_b128 v72, v[30:33] offset:64512
	s_waitcnt lgkmcnt(6)
	v_mfma_f32_32x32x16_bf16 v[114:129], v[54:57], v[58:61], v[114:129]
	s_waitcnt lgkmcnt(4)
	v_mfma_f32_32x32x16_bf16 v[98:113], v[54:57], v[68:71], v[98:113]
	v_mfma_f32_32x32x16_bf16 v[82:97], v[62:65], v[58:61], v[82:97]
	v_mfma_f32_32x32x16_bf16 v[34:49], v[62:65], v[68:71], v[34:49]
	s_cmp_lt_i32 s9, s40
	s_waitcnt lgkmcnt(0)
	s_barrier
	s_cbranch_scc1 .LBB0_3345

.LBB0_3358:
	s_cmp_lg_u32 s22, 0
	s_cbranch_scc1 .Ltrim_LBB0_3358
	s_waitcnt vmcnt(0)
.Ltrim_LBB0_3358:
	s_bitcmp1_b32 s22, 0
	s_cselect_b32 s23, 0x12000, 0
	v_add3_u32 v53, s23, v50, v52
	v_add3_u32 v177, s23, v51, v52
	ds_read_b128 v[54:57], v53
	ds_read_b128 v[58:61], v177 offset:36864
	ds_read_b128 v[80:83], v53 offset:32
	ds_read_b128 v[84:87], v177 offset:36896
	ds_read_b128 v[88:91], v177 offset:41472
	ds_read_b128 v[92:95], v177 offset:41504
	s_waitcnt lgkmcnt(4)
	v_mfma_f32_32x32x16_bf16 v[128:143], v[54:57], v[58:61], v[128:143]
	s_add_i32 s22, s22, 1
	s_bitcmp1_b32 s22, 0
	s_cselect_b32 s23, 0x12000, 0
	v_add_u32_e32 v194, s23, v176
	v_lshl_add_u64 v[62:63], s[20:21], 0, v[38:39]
	v_lshl_add_u64 v[192:193], s[20:21], 0, v[40:41]
	s_waitcnt lgkmcnt(1)
	v_mfma_f32_32x32x16_bf16 v[112:127], v[54:57], v[88:91], v[112:127]
	ds_read_b128 v[54:57], v53 offset:4608
	ds_read_b128 v[188:191], v53 offset:4640
	s_waitcnt vmcnt(4)
	ds_write_b128 v194, v[2:5]
	ds_write_b128 v194, v[6:9] offset:9216
	s_waitcnt lgkmcnt(3)
	v_mfma_f32_32x32x16_bf16 v[96:111], v[54:57], v[58:61], v[96:111]
	v_mfma_f32_32x32x16_bf16 v[64:79], v[54:57], v[88:91], v[64:79]
	v_lshl_add_u64 v[54:55], s[20:21], 0, v[34:35]
	v_lshl_add_u64 v[56:57], s[20:21], 0, v[36:37]
	global_load_dwordx4 v[2:5], v[54:55], off
	v_mfma_f32_32x32x16_bf16 v[128:143], v[80:83], v[84:87], v[128:143]
	v_mfma_f32_32x32x16_bf16 v[112:127], v[80:83], v[92:95], v[112:127]
	ds_read_b128 v[54:57], v53 offset:64
	ds_read_b128 v[58:61], v53 offset:4672
	ds_read_b128 v[80:83], v177 offset:36928
	ds_read_b128 v[88:91], v177 offset:41536
	ds_write_b128 v194, v[10:13] offset:18432
	ds_write_b128 v194, v[14:17] offset:27648
	v_lshl_add_u64 v[62:63], s[20:21], 0, v[42:43]
	s_waitcnt lgkmcnt(8)
	v_mfma_f32_32x32x16_bf16 v[96:111], v[188:191], v[84:87], v[96:111]
	v_mfma_f32_32x32x16_bf16 v[64:79], v[188:191], v[92:95], v[64:79]
	v_lshl_add_u64 v[92:93], s[20:21], 0, v[46:47]
	v_lshl_add_u64 v[94:95], s[20:21], 0, v[44:45]
	v_lshl_add_u64 v[188:189], s[20:21], 0, v[48:49]
	s_waitcnt lgkmcnt(3)
	v_mfma_f32_32x32x16_bf16 v[128:143], v[54:57], v[80:83], v[128:143]
	s_waitcnt lgkmcnt(2)
	v_mfma_f32_32x32x16_bf16 v[112:127], v[54:57], v[88:91], v[112:127]
	v_mfma_f32_32x32x16_bf16 v[96:111], v[58:61], v[80:83], v[96:111]
	v_mfma_f32_32x32x16_bf16 v[64:79], v[58:61], v[88:91], v[64:79]
	ds_read_b128 v[54:57], v53 offset:96
	ds_read_b128 v[58:61], v177 offset:36960
	ds_read_b128 v[80:83], v53 offset:4704
	ds_read_b128 v[84:87], v177 offset:41568
	s_waitcnt vmcnt(4)
	ds_write_b128 v194, v[18:21] offset:36864
	s_waitcnt vmcnt(2)
	ds_write_b128 v194, v[26:29] offset:46080
	s_waitcnt vmcnt(3)
	ds_write_b128 v194, v[22:25] offset:55296
	s_waitcnt vmcnt(1)
	ds_write_b128 v194, v[30:33] offset:64512
	global_load_dwordx4 v[18:21], v[62:63], off
	global_load_dwordx4 v[22:25], v[92:93], off
	global_load_dwordx4 v[26:29], v[94:95], off
	global_load_dwordx4 v[30:33], v[188:189], off
	s_waitcnt lgkmcnt(6)
	v_mfma_f32_32x32x16_bf16 v[128:143], v[54:57], v[58:61], v[128:143]
	s_waitcnt lgkmcnt(4)
	v_mfma_f32_32x32x16_bf16 v[112:127], v[54:57], v[84:87], v[112:127]
	v_mfma_f32_32x32x16_bf16 v[96:111], v[80:83], v[58:61], v[96:111]
	v_mfma_f32_32x32x16_bf16 v[64:79], v[80:83], v[84:87], v[64:79]
	s_add_u32 s20, s20, 0x80
	s_addc_u32 s21, s21, 0
	s_cmp_eq_u32 s11, s22
	s_waitcnt lgkmcnt(0)
	s_barrier
	s_cbranch_scc0 .LBB0_3358
	s_mov_b32 s20, s11
	s_cmp_ge_i32 s20, s9
	s_cbranch_scc0 .LBB0_3362
	s_branch .LBB0_3364

.LBB0_3363:
	s_bitcmp1_b32 s20, 0
	s_cselect_b32 s21, 0x12000, 0
	v_add3_u32 v37, s21, v34, v36
	v_add3_u32 v62, s21, v35, v36
	ds_read_b128 v[38:41], v37
	ds_read_b128 v[42:45], v62 offset:36864
	ds_read_b128 v[46:49], v37 offset:32
	ds_read_b128 v[50:53], v62 offset:36896
	ds_read_b128 v[54:57], v62 offset:41472
	ds_read_b128 v[58:61], v62 offset:41504
	s_waitcnt lgkmcnt(4)
	v_mfma_f32_32x32x16_bf16 v[128:143], v[38:41], v[42:45], v[128:143]
	s_add_i32 s20, s20, 1
	s_bitcmp1_b32 s20, 0
	s_cselect_b32 s21, 0x12000, 0
	s_waitcnt lgkmcnt(1)
	v_mfma_f32_32x32x16_bf16 v[112:127], v[38:41], v[54:57], v[112:127]
	ds_read_b128 v[38:41], v37 offset:4608
	ds_read_b128 v[80:83], v37 offset:4640
	s_waitcnt lgkmcnt(1)
	v_mfma_f32_32x32x16_bf16 v[96:111], v[38:41], v[42:45], v[96:111]
	v_mfma_f32_32x32x16_bf16 v[64:79], v[38:41], v[54:57], v[64:79]
	v_add_u32_e32 v54, s21, v176
	s_waitcnt vmcnt(4)
	ds_write_b128 v54, v[2:5]
	s_waitcnt vmcnt(6)
	ds_write_b128 v54, v[6:9] offset:9216
	ds_read_b128 v[38:41], v37 offset:64
	v_mfma_f32_32x32x16_bf16 v[128:143], v[46:49], v[50:53], v[128:143]
	v_mfma_f32_32x32x16_bf16 v[112:127], v[46:49], v[58:61], v[112:127]
	s_waitcnt lgkmcnt(3)
	v_mfma_f32_32x32x16_bf16 v[96:111], v[80:83], v[50:53], v[96:111]
	ds_read_b128 v[42:45], v37 offset:4672
	ds_read_b128 v[46:49], v62 offset:36928
	ds_read_b128 v[50:53], v62 offset:41536
	s_waitcnt vmcnt(5)
	ds_write_b128 v54, v[10:13] offset:18432
	s_waitcnt vmcnt(4)
	ds_write_b128 v54, v[14:17] offset:27648
	v_mfma_f32_32x32x16_bf16 v[64:79], v[80:83], v[58:61], v[64:79]
	s_waitcnt lgkmcnt(3)
	v_mfma_f32_32x32x16_bf16 v[128:143], v[38:41], v[46:49], v[128:143]
	s_waitcnt lgkmcnt(2)
	v_mfma_f32_32x32x16_bf16 v[112:127], v[38:41], v[50:53], v[112:127]
	v_mfma_f32_32x32x16_bf16 v[96:111], v[42:45], v[46:49], v[96:111]
	v_mfma_f32_32x32x16_bf16 v[64:79], v[42:45], v[50:53], v[64:79]
	ds_read_b128 v[38:41], v37 offset:96
	ds_read_b128 v[42:45], v62 offset:36960
	ds_read_b128 v[46:49], v37 offset:4704
	ds_read_b128 v[50:53], v62 offset:41568
	s_waitcnt vmcnt(3)
	ds_write_b128 v54, v[18:21] offset:36864
	s_waitcnt vmcnt(1)
	ds_write_b128 v54, v[26:29] offset:46080
	ds_write_b128 v54, v[22:25] offset:55296
	s_waitcnt vmcnt(0)
	ds_write_b128 v54, v[30:33] offset:64512
	s_waitcnt lgkmcnt(6)
	v_mfma_f32_32x32x16_bf16 v[128:143], v[38:41], v[42:45], v[128:143]
	s_waitcnt lgkmcnt(4)
	v_mfma_f32_32x32x16_bf16 v[112:127], v[38:41], v[50:53], v[112:127]
	v_mfma_f32_32x32x16_bf16 v[96:111], v[46:49], v[42:45], v[96:111]
	v_mfma_f32_32x32x16_bf16 v[64:79], v[46:49], v[50:53], v[64:79]
	s_cmp_lt_i32 s20, s9
	s_waitcnt lgkmcnt(0)
	s_barrier
	s_cbranch_scc1 .LBB0_3363

.LBB0_3384:
	s_cmp_lg_u32 s35, 0
	s_cbranch_scc1 .Ltrim_LBB0_3384
	s_waitcnt vmcnt(0)
.Ltrim_LBB0_3384:
	s_bitcmp1_b32 s35, 0
	s_cselect_b32 s36, 0x12000, 0
	v_add3_u32 v69, s36, v66, v68
	v_add3_u32 v177, s36, v67, v68
	ds_read_b128 v[70:73], v69
	ds_read_b128 v[74:77], v177 offset:36864
	ds_read_b128 v[96:99], v69 offset:32
	ds_read_b128 v[100:103], v177 offset:36896
	ds_read_b128 v[104:107], v177 offset:41472
	ds_read_b128 v[108:111], v177 offset:41504
	s_waitcnt lgkmcnt(4)
	v_mfma_f32_32x32x16_bf16 v[128:143], v[70:73], v[74:77], v[128:143]
	s_add_i32 s35, s35, 1
	s_bitcmp1_b32 s35, 0
	s_cselect_b32 s36, 0x12000, 0
	v_add_u32_e32 v194, s36, v176
	v_lshl_add_u64 v[78:79], s[14:15], 0, v[38:39]
	v_lshl_add_u64 v[192:193], s[14:15], 0, v[40:41]
	s_waitcnt lgkmcnt(1)
	v_mfma_f32_32x32x16_bf16 v[112:127], v[70:73], v[104:107], v[112:127]
	ds_read_b128 v[70:73], v69 offset:4608
	ds_read_b128 v[188:191], v69 offset:4640
	s_waitcnt vmcnt(4)
	ds_write_b128 v194, v[2:5]
	ds_write_b128 v194, v[6:9] offset:9216
	s_waitcnt lgkmcnt(3)
	v_mfma_f32_32x32x16_bf16 v[80:95], v[70:73], v[74:77], v[80:95]
	v_mfma_f32_32x32x16_bf16 v[48:63], v[70:73], v[104:107], v[48:63]
	v_lshl_add_u64 v[70:71], s[14:15], 0, v[34:35]
	v_lshl_add_u64 v[72:73], s[14:15], 0, v[36:37]
	global_load_dwordx4 v[2:5], v[70:71], off
	v_mfma_f32_32x32x16_bf16 v[128:143], v[96:99], v[100:103], v[128:143]
	v_mfma_f32_32x32x16_bf16 v[112:127], v[96:99], v[108:111], v[112:127]
	ds_read_b128 v[70:73], v69 offset:64
	ds_read_b128 v[74:77], v69 offset:4672
	ds_read_b128 v[96:99], v177 offset:36928
	ds_read_b128 v[104:107], v177 offset:41536
	ds_write_b128 v194, v[10:13] offset:18432
	ds_write_b128 v194, v[14:17] offset:27648
	v_lshl_add_u64 v[78:79], s[14:15], 0, v[42:43]
	s_waitcnt lgkmcnt(8)
	v_mfma_f32_32x32x16_bf16 v[80:95], v[188:191], v[100:103], v[80:95]
	v_mfma_f32_32x32x16_bf16 v[48:63], v[188:191], v[108:111], v[48:63]
	v_lshl_add_u64 v[108:109], s[14:15], 0, v[46:47]
	v_lshl_add_u64 v[110:111], s[14:15], 0, v[44:45]
	v_lshl_add_u64 v[188:189], s[14:15], 0, v[64:65]
	s_waitcnt lgkmcnt(3)
	v_mfma_f32_32x32x16_bf16 v[128:143], v[70:73], v[96:99], v[128:143]
	s_waitcnt lgkmcnt(2)
	v_mfma_f32_32x32x16_bf16 v[112:127], v[70:73], v[104:107], v[112:127]
	v_mfma_f32_32x32x16_bf16 v[80:95], v[74:77], v[96:99], v[80:95]
	v_mfma_f32_32x32x16_bf16 v[48:63], v[74:77], v[104:107], v[48:63]
	ds_read_b128 v[70:73], v69 offset:96
	ds_read_b128 v[74:77], v177 offset:36960
	ds_read_b128 v[96:99], v69 offset:4704
	ds_read_b128 v[100:103], v177 offset:41568
	s_waitcnt vmcnt(4)
	ds_write_b128 v194, v[18:21] offset:36864
	s_waitcnt vmcnt(2)
	ds_write_b128 v194, v[26:29] offset:46080
	s_waitcnt vmcnt(3)
	ds_write_b128 v194, v[22:25] offset:55296
	s_waitcnt vmcnt(1)
	ds_write_b128 v194, v[30:33] offset:64512
	global_load_dwordx4 v[18:21], v[78:79], off
	global_load_dwordx4 v[22:25], v[108:109], off
	global_load_dwordx4 v[26:29], v[110:111], off
	global_load_dwordx4 v[30:33], v[188:189], off
	s_waitcnt lgkmcnt(6)
	v_mfma_f32_32x32x16_bf16 v[128:143], v[70:73], v[74:77], v[128:143]
	s_waitcnt lgkmcnt(4)
	v_mfma_f32_32x32x16_bf16 v[112:127], v[70:73], v[100:103], v[112:127]
	v_mfma_f32_32x32x16_bf16 v[80:95], v[96:99], v[74:77], v[80:95]
	v_mfma_f32_32x32x16_bf16 v[48:63], v[96:99], v[100:103], v[48:63]
	s_add_u32 s14, s14, 0x80
	s_addc_u32 s15, s15, 0
	s_cmp_eq_u32 s34, s35
	s_waitcnt lgkmcnt(0)
	s_barrier
	s_cbranch_scc0 .LBB0_3384
	s_mov_b32 s14, s34
	s_cmp_ge_i32 s14, s33
	s_cbranch_scc0 .LBB0_3387
	s_branch .LBB0_3389

.LBB0_3388:
	s_bitcmp1_b32 s14, 0
	s_cselect_b32 s15, 0x12000, 0
	v_add3_u32 v37, s15, v34, v36
	v_add3_u32 v46, s15, v35, v36
	ds_read_b128 v[38:41], v37
	ds_read_b128 v[42:45], v46 offset:36864
	ds_read_b128 v[64:67], v37 offset:32
	ds_read_b128 v[68:71], v46 offset:36896
	ds_read_b128 v[72:75], v46 offset:41472
	ds_read_b128 v[76:79], v46 offset:41504
	s_waitcnt lgkmcnt(4)
	v_mfma_f32_32x32x16_bf16 v[128:143], v[38:41], v[42:45], v[128:143]
	s_add_i32 s14, s14, 1
	s_bitcmp1_b32 s14, 0
	s_cselect_b32 s15, 0x12000, 0
	v_add_u32_e32 v47, s15, v176
	s_waitcnt lgkmcnt(1)
	v_mfma_f32_32x32x16_bf16 v[112:127], v[38:41], v[72:75], v[112:127]
	ds_read_b128 v[38:41], v37 offset:4608
	ds_read_b128 v[96:99], v37 offset:4640
	s_waitcnt vmcnt(4)
	ds_write_b128 v47, v[2:5]
	s_waitcnt vmcnt(6)
	ds_write_b128 v47, v[6:9] offset:9216
	s_waitcnt lgkmcnt(3)
	v_mfma_f32_32x32x16_bf16 v[80:95], v[38:41], v[42:45], v[80:95]
	v_mfma_f32_32x32x16_bf16 v[48:63], v[38:41], v[72:75], v[48:63]
	ds_read_b128 v[38:41], v37 offset:64
	v_mfma_f32_32x32x16_bf16 v[128:143], v[64:67], v[68:71], v[128:143]
	v_mfma_f32_32x32x16_bf16 v[112:127], v[64:67], v[76:79], v[112:127]
	s_waitcnt lgkmcnt(3)
	v_mfma_f32_32x32x16_bf16 v[80:95], v[96:99], v[68:71], v[80:95]
	ds_read_b128 v[42:45], v37 offset:4672
	ds_read_b128 v[64:67], v46 offset:36928
	ds_read_b128 v[68:71], v46 offset:41536
	s_waitcnt vmcnt(5)
	ds_write_b128 v47, v[10:13] offset:18432
	s_waitcnt vmcnt(4)
	ds_write_b128 v47, v[14:17] offset:27648
	v_mfma_f32_32x32x16_bf16 v[48:63], v[96:99], v[76:79], v[48:63]
	s_waitcnt lgkmcnt(3)
	v_mfma_f32_32x32x16_bf16 v[128:143], v[38:41], v[64:67], v[128:143]
	s_waitcnt lgkmcnt(2)
	v_mfma_f32_32x32x16_bf16 v[112:127], v[38:41], v[68:71], v[112:127]
	v_mfma_f32_32x32x16_bf16 v[80:95], v[42:45], v[64:67], v[80:95]
	v_mfma_f32_32x32x16_bf16 v[48:63], v[42:45], v[68:71], v[48:63]
	ds_read_b128 v[38:41], v37 offset:96
	ds_read_b128 v[42:45], v46 offset:36960
	ds_read_b128 v[64:67], v37 offset:4704
	ds_read_b128 v[68:71], v46 offset:41568
	s_waitcnt vmcnt(3)
	ds_write_b128 v47, v[18:21] offset:36864
	s_waitcnt vmcnt(1)
	ds_write_b128 v47, v[26:29] offset:46080
	ds_write_b128 v47, v[22:25] offset:55296
	s_waitcnt vmcnt(0)
	ds_write_b128 v47, v[30:33] offset:64512
	s_waitcnt lgkmcnt(6)
	v_mfma_f32_32x32x16_bf16 v[128:143], v[38:41], v[42:45], v[128:143]
	s_waitcnt lgkmcnt(4)
	v_mfma_f32_32x32x16_bf16 v[112:127], v[38:41], v[68:71], v[112:127]
	v_mfma_f32_32x32x16_bf16 v[80:95], v[64:67], v[42:45], v[80:95]
	v_mfma_f32_32x32x16_bf16 v[48:63], v[64:67], v[68:71], v[48:63]
	s_cmp_lt_i32 s14, s33
	s_waitcnt lgkmcnt(0)
	s_barrier
	s_cbranch_scc1 .LBB0_3388

.LBB0_3399:
	s_cmp_lg_u32 s14, 0
	s_cbranch_scc1 .Ltrim_LBB0_3399
	s_waitcnt vmcnt(0)
.Ltrim_LBB0_3399:
	s_bitcmp1_b32 s14, 0
	s_cselect_b32 s15, 0x12000, 0
	v_add3_u32 v53, s15, v50, v52
	v_add3_u32 v177, s15, v51, v52
	ds_read_b128 v[54:57], v53
	ds_read_b128 v[58:61], v177 offset:36864
	ds_read_b128 v[62:65], v53 offset:32
	ds_read_b128 v[66:69], v177 offset:36896
	ds_read_b128 v[70:73], v177 offset:41472
	ds_read_b128 v[74:77], v177 offset:41504
	s_waitcnt lgkmcnt(4)
	v_mfma_f32_32x32x16_bf16 v[128:143], v[54:57], v[58:61], v[128:143]
	s_add_i32 s14, s14, 1
	s_bitcmp1_b32 s14, 0
	s_cselect_b32 s15, 0x12000, 0
	v_add_u32_e32 v194, s15, v176
	v_lshl_add_u64 v[78:79], s[12:13], 0, v[38:39]
	v_lshl_add_u64 v[192:193], s[12:13], 0, v[40:41]
	s_waitcnt lgkmcnt(1)
	v_mfma_f32_32x32x16_bf16 v[112:127], v[54:57], v[70:73], v[112:127]
	ds_read_b128 v[54:57], v53 offset:4608
	ds_read_b128 v[188:191], v53 offset:4640
	s_waitcnt vmcnt(4)
	ds_write_b128 v194, v[2:5]
	ds_write_b128 v194, v[6:9] offset:9216
	s_waitcnt lgkmcnt(3)
	v_mfma_f32_32x32x16_bf16 v[96:111], v[54:57], v[58:61], v[96:111]
	v_mfma_f32_32x32x16_bf16 v[80:95], v[54:57], v[70:73], v[80:95]
	v_lshl_add_u64 v[54:55], s[12:13], 0, v[34:35]
	v_lshl_add_u64 v[56:57], s[12:13], 0, v[36:37]
	global_load_dwordx4 v[2:5], v[54:55], off
	v_mfma_f32_32x32x16_bf16 v[128:143], v[62:65], v[66:69], v[128:143]
	v_mfma_f32_32x32x16_bf16 v[112:127], v[62:65], v[74:77], v[112:127]
	ds_read_b128 v[54:57], v53 offset:64
	ds_read_b128 v[58:61], v53 offset:4672
	ds_read_b128 v[62:65], v177 offset:36928
	ds_read_b128 v[70:73], v177 offset:41536
	ds_write_b128 v194, v[10:13] offset:18432
	ds_write_b128 v194, v[14:17] offset:27648
	v_lshl_add_u64 v[78:79], s[12:13], 0, v[44:45]
	s_waitcnt lgkmcnt(8)
	v_mfma_f32_32x32x16_bf16 v[96:111], v[188:191], v[66:69], v[96:111]
	v_mfma_f32_32x32x16_bf16 v[80:95], v[188:191], v[74:77], v[80:95]
	v_lshl_add_u64 v[74:75], s[12:13], 0, v[42:43]
	v_lshl_add_u64 v[76:77], s[12:13], 0, v[46:47]
	v_lshl_add_u64 v[188:189], s[12:13], 0, v[48:49]
	s_waitcnt lgkmcnt(3)
	v_mfma_f32_32x32x16_bf16 v[128:143], v[54:57], v[62:65], v[128:143]
	s_waitcnt lgkmcnt(2)
	v_mfma_f32_32x32x16_bf16 v[112:127], v[54:57], v[70:73], v[112:127]
	v_mfma_f32_32x32x16_bf16 v[96:111], v[58:61], v[62:65], v[96:111]
	v_mfma_f32_32x32x16_bf16 v[80:95], v[58:61], v[70:73], v[80:95]
	ds_read_b128 v[54:57], v53 offset:96
	ds_read_b128 v[58:61], v177 offset:36960
	ds_read_b128 v[62:65], v53 offset:4704
	ds_read_b128 v[66:69], v177 offset:41568
	s_waitcnt vmcnt(4)
	ds_write_b128 v194, v[18:21] offset:36864
	s_waitcnt vmcnt(2)
	ds_write_b128 v194, v[26:29] offset:46080
	s_waitcnt vmcnt(3)
	ds_write_b128 v194, v[22:25] offset:55296
	s_waitcnt vmcnt(1)
	ds_write_b128 v194, v[30:33] offset:64512
	global_load_dwordx4 v[18:21], v[74:75], off
	global_load_dwordx4 v[22:25], v[76:77], off
	global_load_dwordx4 v[26:29], v[78:79], off
	global_load_dwordx4 v[30:33], v[188:189], off
	s_waitcnt lgkmcnt(6)
	v_mfma_f32_32x32x16_bf16 v[128:143], v[54:57], v[58:61], v[128:143]
	s_waitcnt lgkmcnt(4)
	v_mfma_f32_32x32x16_bf16 v[112:127], v[54:57], v[66:69], v[112:127]
	v_mfma_f32_32x32x16_bf16 v[96:111], v[62:65], v[58:61], v[96:111]
	v_mfma_f32_32x32x16_bf16 v[80:95], v[62:65], v[66:69], v[80:95]
	s_add_u32 s12, s12, 0x80
	s_addc_u32 s13, s13, 0
	s_cmp_eq_u32 s7, s14
	s_waitcnt lgkmcnt(0)
	s_barrier
	s_cbranch_scc0 .LBB0_3399
	s_mov_b32 s12, s7
	s_cmp_ge_i32 s12, s1
	s_cbranch_scc0 .LBB0_3403
	s_branch .LBB0_3405

.LBB0_3404:
	s_bitcmp1_b32 s12, 0
	s_cselect_b32 s13, 0x12000, 0
	v_add3_u32 v37, s13, v34, v36
	v_add3_u32 v66, s13, v35, v36
	ds_read_b128 v[38:41], v37
	ds_read_b128 v[42:45], v66 offset:36864
	ds_read_b128 v[46:49], v37 offset:32
	ds_read_b128 v[50:53], v66 offset:36896
	ds_read_b128 v[54:57], v66 offset:41472
	ds_read_b128 v[58:61], v66 offset:41504
	s_waitcnt lgkmcnt(4)
	v_mfma_f32_32x32x16_bf16 v[128:143], v[38:41], v[42:45], v[128:143]
	s_add_i32 s12, s12, 1
	s_bitcmp1_b32 s12, 0
	s_cselect_b32 s13, 0x12000, 0
	s_waitcnt lgkmcnt(1)
	v_mfma_f32_32x32x16_bf16 v[112:127], v[38:41], v[54:57], v[112:127]
	ds_read_b128 v[38:41], v37 offset:4608
	ds_read_b128 v[62:65], v37 offset:4640
	s_waitcnt lgkmcnt(1)
	v_mfma_f32_32x32x16_bf16 v[96:111], v[38:41], v[42:45], v[96:111]
	v_mfma_f32_32x32x16_bf16 v[80:95], v[38:41], v[54:57], v[80:95]
	v_add_u32_e32 v54, s13, v176
	s_waitcnt vmcnt(4)
	ds_write_b128 v54, v[2:5]
	s_waitcnt vmcnt(6)
	ds_write_b128 v54, v[6:9] offset:9216
	ds_read_b128 v[38:41], v37 offset:64
	v_mfma_f32_32x32x16_bf16 v[128:143], v[46:49], v[50:53], v[128:143]
	v_mfma_f32_32x32x16_bf16 v[112:127], v[46:49], v[58:61], v[112:127]
	s_waitcnt lgkmcnt(3)
	v_mfma_f32_32x32x16_bf16 v[96:111], v[62:65], v[50:53], v[96:111]
	ds_read_b128 v[42:45], v37 offset:4672
	ds_read_b128 v[46:49], v66 offset:36928
	ds_read_b128 v[50:53], v66 offset:41536
	s_waitcnt vmcnt(5)
	ds_write_b128 v54, v[10:13] offset:18432
	s_waitcnt vmcnt(4)
	ds_write_b128 v54, v[14:17] offset:27648
	v_mfma_f32_32x32x16_bf16 v[80:95], v[62:65], v[58:61], v[80:95]
	s_waitcnt lgkmcnt(3)
	v_mfma_f32_32x32x16_bf16 v[128:143], v[38:41], v[46:49], v[128:143]
	s_waitcnt lgkmcnt(2)
	v_mfma_f32_32x32x16_bf16 v[112:127], v[38:41], v[50:53], v[112:127]
	v_mfma_f32_32x32x16_bf16 v[96:111], v[42:45], v[46:49], v[96:111]
	v_mfma_f32_32x32x16_bf16 v[80:95], v[42:45], v[50:53], v[80:95]
	ds_read_b128 v[38:41], v37 offset:96
	ds_read_b128 v[42:45], v66 offset:36960
	ds_read_b128 v[46:49], v37 offset:4704
	ds_read_b128 v[50:53], v66 offset:41568
	s_waitcnt vmcnt(3)
	ds_write_b128 v54, v[18:21] offset:36864
	s_waitcnt vmcnt(1)
	ds_write_b128 v54, v[26:29] offset:46080
	ds_write_b128 v54, v[22:25] offset:55296
	s_waitcnt vmcnt(0)
	ds_write_b128 v54, v[30:33] offset:64512
	s_waitcnt lgkmcnt(6)
	v_mfma_f32_32x32x16_bf16 v[128:143], v[38:41], v[42:45], v[128:143]
	s_waitcnt lgkmcnt(4)
	v_mfma_f32_32x32x16_bf16 v[112:127], v[38:41], v[50:53], v[112:127]
	v_mfma_f32_32x32x16_bf16 v[96:111], v[46:49], v[42:45], v[96:111]
	v_mfma_f32_32x32x16_bf16 v[80:95], v[46:49], v[50:53], v[80:95]
	s_cmp_lt_i32 s12, s1
	s_waitcnt lgkmcnt(0)
	s_barrier
	s_cbranch_scc1 .LBB0_3404

.LBB0_3413:
	s_waitcnt vmcnt(3)
	v_mov_b32_e32 v0, v208
	s_mov_b32 s101, 0
	s_cmp_lt_u32 s86, 4
	s_cselect_b32 s8, 0x420, s86
	v_readlane_b32 s44, v239, 4
	s_cmpk_gt_i32 s8, 0x41f
	v_readfirstlane_b32 s0, v0
	v_readlane_b32 s52, v239, 12
	v_readlane_b32 s53, v239, 13
	v_readlane_b32 s54, v239, 14
	v_readlane_b32 s55, v239, 15
	v_readlane_b32 s56, v239, 16
	v_readlane_b32 s57, v239, 17
	v_readlane_b32 s58, v239, 18
	v_readlane_b32 s59, v239, 19
	v_readlane_b32 s45, v239, 5
	v_readlane_b32 s46, v239, 6
	v_readlane_b32 s47, v239, 7
	v_readlane_b32 s48, v239, 8
	v_readlane_b32 s49, v239, 9
	v_readlane_b32 s50, v239, 10
	v_readlane_b32 s51, v239, 11
	s_cbranch_scc1 .LBB0_3523
	s_bfe_u32 s9, s0, 0x10008
	s_lshl_b32 s0, s8, 1
	s_mul_i32 s10, s9, 0x12200
	s_or_b32 s11, s0, s9
	s_lshl_b32 s12, s92, 1
	s_movk_i32 s13, 0xb00
	v_mov_b32_e32 v1, 0
	s_movk_i32 s14, 0x400
	s_movk_i32 s15, 0x1600
	s_waitcnt vmcnt(2)
	v_mov_b32_e32 v6, 3
	s_branch .LBB0_3417

.LBB0_3416:
	s_add_i32 s8, s8, s92
	s_add_i32 s11, s11, s12
	s_cmp_eq_u32 s101, 1
	s_cbranch_scc1 .LBB0_3523
	s_cmpk_lt_i32 s8, 0x420
	s_cbranch_scc1 .LBB0_3417
	s_sub_u32 s98, s86, 32
	s_cmp_lt_u32 s98, 20
	s_cbranch_scc0 .LBB0_3523
	s_mov_b32 s101, 1
	s_and_b32 s8, s98, 3
	s_lshr_b32 s99, s98, 2
	s_lshl_b32 s99, s99, 8
	s_add_u32 s8, s8, s99
	v_readfirstlane_b32 s99, v208
	s_nop 3
	s_bfe_u32 s99, s99, 0x10008
	s_lshl_b32 s11, s8, 1
	s_or_b32 s11, s11, s99

	.amdhsa_kernel _Z6k_mega1P
		.amdhsa_group_segment_fixed_size 148560
		.amdhsa_private_segment_fixed_size 0
		.amdhsa_kernarg_size 464
		.amdhsa_user_sgpr_count 2
		.amdhsa_user_sgpr_dispatch_ptr 0
		.amdhsa_user_sgpr_queue_ptr 0
		.amdhsa_user_sgpr_kernarg_segment_ptr 1
		.amdhsa_user_sgpr_dispatch_id 0
		.amdhsa_user_sgpr_kernarg_preload_length 0
		.amdhsa_user_sgpr_kernarg_preload_offset 0
		.amdhsa_user_sgpr_private_segment_size 0
		.amdhsa_uses_dynamic_stack 0
		.amdhsa_enable_private_segment 0
		.amdhsa_system_sgpr_workgroup_id_x 1
		.amdhsa_system_sgpr_workgroup_id_y 0
		.amdhsa_system_sgpr_workgroup_id_z 0
		.amdhsa_system_sgpr_workgroup_info 0
		.amdhsa_system_vgpr_workitem_id 2
		.amdhsa_next_free_vgpr 256
		.amdhsa_next_free_sgpr 102
		.amdhsa_accum_offset 256
		.amdhsa_reserve_vcc 1
		.amdhsa_float_round_mode_32 0
		.amdhsa_float_round_mode_16_64 0
		.amdhsa_float_denorm_mode_32 3
		.amdhsa_float_denorm_mode_16_64 3
		.amdhsa_dx10_clamp 1
		.amdhsa_ieee_mode 1
		.amdhsa_fp16_overflow 0
		.amdhsa_tg_split 0
		.amdhsa_exception_fp_ieee_invalid_op 0
		.amdhsa_exception_fp_denorm_src 0
		.amdhsa_exception_fp_ieee_div_zero 0
		.amdhsa_exception_fp_ieee_overflow 0
		.amdhsa_exception_fp_ieee_underflow 0
		.amdhsa_exception_fp_ieee_inexact 0
		.amdhsa_exception_int_div_zero 0
	.end_amdhsa_kernel

amdhsa.kernels:
  - .agpr_count:     0
    .args:
      - .offset:         0
        .size:           208
        .value_kind:     by_value
      - .offset:         208
        .size:           4
        .value_kind:     hidden_block_count_x
      - .offset:         212
        .size:           4
        .value_kind:     hidden_block_count_y
      - .offset:         216
        .size:           4
        .value_kind:     hidden_block_count_z
      - .offset:         220
        .size:           2
        .value_kind:     hidden_group_size_x
      - .offset:         222
        .size:           2
        .value_kind:     hidden_group_size_y
      - .offset:         224
        .size:           2
        .value_kind:     hidden_group_size_z
      - .offset:         226
        .size:           2
        .value_kind:     hidden_remainder_x
      - .offset:         228
        .size:           2
        .value_kind:     hidden_remainder_y
      - .offset:         230
        .size:           2
        .value_kind:     hidden_remainder_z
      - .offset:         248
        .size:           8
        .value_kind:     hidden_global_offset_x
      - .offset:         256
        .size:           8
        .value_kind:     hidden_global_offset_y
      - .offset:         264
        .size:           8
        .value_kind:     hidden_global_offset_z
      - .offset:         272
        .size:           2
        .value_kind:     hidden_grid_dims
      - .offset:         296
        .size:           8
        .value_kind:     hidden_multigrid_sync_arg
    .group_segment_fixed_size: 148560
    .kernarg_segment_align: 8
    .kernarg_segment_size: 464
    .language:       OpenCL C
    .language_version:
      - 2
      - 0
    .max_flat_workgroup_size: 512
    .name:           _Z6k_mega1P
    .private_segment_fixed_size: 0
    .sgpr_count:     108
    .sgpr_spill_count: 30
    .symbol:         _Z6k_mega1P.kd
    .uniform_work_group_size: 1
    .uses_dynamic_stack: false
    .vgpr_count:     256
    .vgpr_spill_count: 0
    .wavefront_size: 64
